# attention: end-of-job normalisation factor computed at the end of the job's last step (PV MFMA shadow) instead of at the head of the next step's finalize
# baseline (speedup 1.0000x reference)
; __device__ __forceinline__ void attn_chain(LAS unsigned char* lds, const bf16* Qb, const bf16* Kb, const bf16* Vb, bf16* Ob, float* lseb, int g0, int wave, int lane) {
;     ...
;     for (int s = 0; s < NSTEP; ++s) {
;         const int rel = s - cw; const bool act = rel >= 0 && rel < 5 * NJOB;
;         const int n = act ? rel / 5 : 0, t = act ? rel - 5 * n : 3;
.LBB0_642:
	s_cmp_lt_u32 s84, 30
	s_cbranch_scc0 .Lattn_nohoist
	s_cmp_eq_u32 s15, 4
	s_cbranch_scc0 .Lattn_nohoist
	v_mov_b32_e32 v245, v182
	v_mov_b32_e32 v246, v182
	s_nop 1
	v_permlane32_swap_b32_e32 v245, v246
	s_nop 1
	v_add_f32_e32 v244, v246, v245
	v_div_scale_f32 v247, s[90:91], v244, v244, 1.0
	v_rcp_f32_e32 v248, v247
	s_nop 1
	v_fma_f32 v249, -v247, v248, 1.0
	v_fmac_f32_e32 v248, v249, v248
	v_div_scale_f32 v249, vcc, 1.0, v244, 1.0
	v_mul_f32_e32 v250, v249, v248
	v_fma_f32 v251, -v247, v250, v249
	v_fmac_f32_e32 v250, v251, v248
	v_fma_f32 v247, -v247, v250, v249
	v_div_fmas_f32 v247, v247, v248, v250
	v_div_fixup_f32 v205, v247, v244, 1.0

.LBB0_691:
	s_andn2_b64 vcc, exec, s[6:7]
	s_cbranch_vccnz .LBB0_642
	s_and_b64 s[6:7], s[70:71], s[72:73]
	s_andn2_b64 vcc, exec, s[6:7]
	s_lshl_b32 s2, s2, 3
	s_cbranch_vccnz .LBB0_696
	s_add_i32 s3, s80, s2
	s_ashr_i32 s6, s3, 7
	s_lshl_b32 s7, s6, 1
	s_sub_i32 s12, 7, s7
	s_and_b32 s13, s3, 0x7f
	s_lshr_b32 s31, s13, s12
	s_lshl_b32 s12, -1, s12
	s_andn2_b32 s3, s3, s12
	v_lshl_or_b32 v64, s3, 5, v157
	v_lshlrev_b32_e32 v64, s7, v64
	s_ashr_i32 s7, s6, 31
	v_add_u32_e32 v64, s31, v64
	v_mov_b32_e32 v66, v244
	v_mov_b32_e32 v68, v205
	s_lshl_b64 s[12:13], s[6:7], 25
	s_add_u32 s12, s28, s12
	v_ashrrev_i32_e32 v65, 31, v64
	v_pk_mul_f32 v[48:49], v[48:49], v[68:69] op_sel_hi:[1,0]
	v_pk_mul_f32 v[50:51], v[50:51], v[68:69] op_sel_hi:[1,0]
	v_pk_mul_f32 v[32:33], v[32:33], v[68:69] op_sel_hi:[1,0]
	v_pk_mul_f32 v[34:35], v[34:35], v[68:69] op_sel_hi:[1,0]
	v_pk_mul_f32 v[16:17], v[16:17], v[68:69] op_sel_hi:[1,0]
	v_pk_mul_f32 v[18:19], v[18:19], v[68:69] op_sel_hi:[1,0]
	v_pk_mul_f32 v[0:1], v[0:1], v[68:69] op_sel_hi:[1,0]
	v_pk_mul_f32 v[2:3], v[2:3], v[68:69] op_sel_hi:[1,0]
	s_addc_u32 s13, s57, s13
	v_lshlrev_b64 v[70:71], 11, v[64:65]
	v_cvt_pk_bf16_f32 v48, v48, v49
	v_cvt_pk_bf16_f32 v49, v50, v51
	v_pk_mul_f32 v[50:51], v[52:53], v[68:69] op_sel_hi:[1,0]
	v_pk_mul_f32 v[52:53], v[54:55], v[68:69] op_sel_hi:[1,0]
	v_cvt_pk_bf16_f32 v32, v32, v33
	v_cvt_pk_bf16_f32 v33, v34, v35
	v_pk_mul_f32 v[34:35], v[36:37], v[68:69] op_sel_hi:[1,0]
	v_pk_mul_f32 v[36:37], v[38:39], v[68:69] op_sel_hi:[1,0]
	v_cvt_pk_bf16_f32 v16, v16, v17
	v_cvt_pk_bf16_f32 v17, v18, v19
	v_pk_mul_f32 v[18:19], v[20:21], v[68:69] op_sel_hi:[1,0]
	v_pk_mul_f32 v[20:21], v[22:23], v[68:69] op_sel_hi:[1,0]
	v_cvt_pk_bf16_f32 v0, v0, v1
	v_cvt_pk_bf16_f32 v1, v2, v3
	v_pk_mul_f32 v[2:3], v[4:5], v[68:69] op_sel_hi:[1,0]
	v_pk_mul_f32 v[4:5], v[6:7], v[68:69] op_sel_hi:[1,0]
	v_lshl_add_u64 v[70:71], s[12:13], 0, v[70:71]
	v_cvt_pk_bf16_f32 v50, v50, v51
	v_cvt_pk_bf16_f32 v51, v52, v53
	v_cvt_pk_bf16_f32 v34, v34, v35
	v_cvt_pk_bf16_f32 v35, v36, v37
	v_cvt_pk_bf16_f32 v18, v18, v19
	v_cvt_pk_bf16_f32 v19, v20, v21
	v_cvt_pk_bf16_f32 v2, v2, v3
	v_cvt_pk_bf16_f32 v3, v4, v5
	v_lshl_add_u64 v[70:71], v[144:145], 1, v[70:71]
	v_permlane32_swap_b32_e32 v48, v50
	v_permlane32_swap_b32_e32 v49, v51
	v_permlane32_swap_b32_e32 v32, v34
	v_permlane32_swap_b32_e32 v33, v35
	v_permlane32_swap_b32_e32 v16, v18
	v_permlane32_swap_b32_e32 v17, v19
	v_permlane32_swap_b32_e32 v0, v2
	v_permlane32_swap_b32_e32 v1, v3
	global_store_dwordx4 v[70:71], v[48:51], off
	global_store_dwordx4 v[70:71], v[32:35], off offset:64
	global_store_dwordx4 v[70:71], v[16:19], off offset:128
	v_pk_mul_f32 v[48:49], v[56:57], v[68:69] op_sel_hi:[1,0]
	v_pk_mul_f32 v[50:51], v[58:59], v[68:69] op_sel_hi:[1,0]
	v_pk_mul_f32 v[32:33], v[40:41], v[68:69] op_sel_hi:[1,0]
	v_pk_mul_f32 v[34:35], v[42:43], v[68:69] op_sel_hi:[1,0]
	v_pk_mul_f32 v[16:17], v[24:25], v[68:69] op_sel_hi:[1,0]
	v_pk_mul_f32 v[18:19], v[26:27], v[68:69] op_sel_hi:[1,0]
	global_store_dwordx4 v[70:71], v[0:3], off offset:192
	v_cvt_pk_bf16_f32 v48, v48, v49
	v_cvt_pk_bf16_f32 v49, v50, v51
	v_pk_mul_f32 v[0:1], v[8:9], v[68:69] op_sel_hi:[1,0]
	v_pk_mul_f32 v[2:3], v[10:11], v[68:69] op_sel_hi:[1,0]
	v_pk_mul_f32 v[50:51], v[60:61], v[68:69] op_sel_hi:[1,0]
	v_pk_mul_f32 v[52:53], v[62:63], v[68:69] op_sel_hi:[1,0]
	v_cvt_pk_bf16_f32 v32, v32, v33
	v_cvt_pk_bf16_f32 v33, v34, v35
	v_pk_mul_f32 v[34:35], v[44:45], v[68:69] op_sel_hi:[1,0]
	v_pk_mul_f32 v[36:37], v[46:47], v[68:69] op_sel_hi:[1,0]
	v_cvt_pk_bf16_f32 v16, v16, v17
	v_cvt_pk_bf16_f32 v17, v18, v19
	v_pk_mul_f32 v[18:19], v[28:29], v[68:69] op_sel_hi:[1,0]
	v_pk_mul_f32 v[20:21], v[30:31], v[68:69] op_sel_hi:[1,0]
	v_cvt_pk_bf16_f32 v0, v0, v1
	v_cvt_pk_bf16_f32 v1, v2, v3
	v_pk_mul_f32 v[2:3], v[12:13], v[68:69] op_sel_hi:[1,0]
	v_pk_mul_f32 v[4:5], v[14:15], v[68:69] op_sel_hi:[1,0]
	v_cvt_pk_bf16_f32 v50, v50, v51
	v_cvt_pk_bf16_f32 v51, v52, v53
	v_cvt_pk_bf16_f32 v34, v34, v35
	v_cvt_pk_bf16_f32 v35, v36, v37
	v_cvt_pk_bf16_f32 v18, v18, v19
	v_cvt_pk_bf16_f32 v19, v20, v21
	v_cvt_pk_bf16_f32 v2, v2, v3
	v_cvt_pk_bf16_f32 v3, v4, v5
	v_permlane32_swap_b32_e32 v48, v50
	v_permlane32_swap_b32_e32 v49, v51
	v_permlane32_swap_b32_e32 v32, v34
	v_permlane32_swap_b32_e32 v33, v35
	v_permlane32_swap_b32_e32 v16, v18
	v_permlane32_swap_b32_e32 v17, v19
	v_permlane32_swap_b32_e32 v0, v2
	v_permlane32_swap_b32_e32 v1, v3
	global_store_dwordx4 v[70:71], v[48:51], off offset:32
	global_store_dwordx4 v[70:71], v[32:35], off offset:96
	global_store_dwordx4 v[70:71], v[16:19], off offset:160
	global_store_dwordx4 v[70:71], v[0:3], off offset:224
	s_and_saveexec_b64 s[70:71], s[4:5]
	s_cbranch_execz .LBB0_695
	v_cmp_gt_f32_e32 vcc, s93, v66
	s_lshl_b64 s[6:7], s[6:7], 19
	s_add_u32 s6, s22, s6
	v_cndmask_b32_e64 v0, 0, 32, vcc
	v_ldexp_f32 v0, v66, v0
	v_log_f32_e32 v2, v0
	v_cndmask_b32_e32 v3, 0, v236, vcc
	s_addc_u32 s7, s23, s7
	v_lshlrev_b64 v[0:1], 5, v[64:65]
	v_sub_f32_e32 v2, v2, v3
	v_lshl_add_u64 v[0:1], s[6:7], 0, v[0:1]
	v_add_f32_e32 v2, v149, v2
	global_store_dword v[0:1], v2, off
